# shift-based tile decode also in FFN2 and branch GEMM unit loops
# speedup vs baseline: 1.0080x; 1.0009x over previous
;     __device__ bool next(int i, pg8::Unit& u) const { const int j = i / 3, n = i - 3 * j; pg8::Unit t; if (!S4.next(j, t)) return false; u.pm = t.pm; u.pn = n * 4 + t.pn; return true; }
;     __host__ __device__ bool next(int i, Unit& u) const {
;         const long L = (long)i * G + c; if (L >= nwg) return false;
;         int wgid = (int)L; { const int q = nwg / NXCD, r = nwg % NXCD, xcd = wgid % NXCD, off = wgid / NXCD; wgid = (xcd < r ? xcd * (q + 1) : r * (q + 1) + (xcd - r) * q) + off; }
;         const int nig = WGM * nN, gid = wgid / nig, fm = gid * WGM, gsz = (nM - fm) < WGM ? (nM - fm) : WGM;
;         u.pm = fm + ((wgid % nig) % gsz); u.pn = (wgid % nig) / gsz; return true;
;     }
.LBB0_325:
	s_ashr_i32 s2, s8, 3
	s_add_i32 s2, s14, s2
	s_ashr_i32 s3, s2, 31
	s_lshr_b32 s3, s3, 28
	s_add_i32 s3, s2, s3
	s_ashr_i32 s8, s3, 4
	s_lshl_b32 s8, s8, 2
	s_and_b32 s3, s3, -16
	s_sub_i32 s2, s2, s3
	s_lshr_b32 s29, s2, 2
	s_and_b32 s2, s2, 3
	s_add_i32 s30, s8, s2

;     __host__ __device__ bool next(int i, Unit& u) const {
;         const long L = (long)i * G + c; if (L >= nwg) return false;
;         int wgid = (int)L; { const int q = nwg / NXCD, r = nwg % NXCD, xcd = wgid % NXCD, off = wgid / NXCD; wgid = (xcd < r ? xcd * (q + 1) : r * (q + 1) + (xcd - r) * q) + off; }
;         const int nig = WGM * nN, gid = wgid / nig, fm = gid * WGM, gsz = (nM - fm) < WGM ? (nM - fm) : WGM;
;         u.pm = fm + ((wgid % nig) % gsz); u.pn = (wgid % nig) / gsz; return true;
;     }
;     __device__ bool next(int i, pg8::Unit& u) const { const int j = i / 3, n = i - 3 * j; pg8::Unit t; if (!S4.next(j, t)) return false; u.pm = t.pm; u.pn = n * 4 + t.pn; return true; }
.LBB0_1316:
	s_ashr_i32 s2, s8, 3
	s_add_i32 s2, s10, s2
	s_ashr_i32 s3, s2, 31
	s_lshr_b32 s3, s3, 28
	s_add_i32 s3, s2, s3
	s_ashr_i32 s8, s3, 4
	s_lshl_b32 s10, s8, 2
	s_and_b32 s3, s3, -16
	s_sub_i32 s2, s2, s3
	s_mul_i32 s9, s9, -3
	s_add_i32 s9, s9, s27
	s_lshl_b32 s9, s9, 2
	s_lshr_b32 s3, s2, 2
	s_add_i32 s8, s3, s9
	s_and_b32 s2, s2, 3
	s_add_i32 s28, s10, s2
